# P1 GEMM on 240 WGs, 16 converter WGs run 24576 deferred items (192/wave); PLE GEMM in P3b
# baseline (speedup 1.0000x reference)
.LBB0_9:
	s_cmp_lg_u32 s101, 0
	s_cbranch_scc1 .Lcv_go
	s_cmp_lt_i32 s80, 0x14a80
	s_cbranch_scc1 .Lcv_go
	s_cmp_lt_i32 s80, 0x1aa80
	s_cbranch_scc1 .LBB0_8

.LBB0_399:
	s_cmpk_eq_i32 s88, 0x100
	s_cselect_b64 s[0:1], -1, 0
	s_cmpk_lg_i32 s88, 0x100
	v_writelane_b32 v250, s0, 23
	s_cselect_b64 s[22:23], -1, 0
	s_cmp_lt_i32 s2, s99
	v_writelane_b32 v250, s1, 24
	s_cselect_b64 s[0:1], -1, 0
	s_or_b64 s[0:1], s[0:1], s[22:23]
	s_and_b64 vcc, exec, s[0:1]
	s_cbranch_vccnz .LBB0_416
	v_writelane_b32 v248, s0, 0
	v_writelane_b32 v248, s1, 1
	v_writelane_b32 v248, s2, 2
	v_writelane_b32 v248, s3, 3
	v_writelane_b32 v248, s4, 4
	v_writelane_b32 v248, s5, 5
	v_writelane_b32 v248, s6, 6
	v_writelane_b32 v248, s7, 7
	v_writelane_b32 v248, s8, 8
	v_writelane_b32 v248, s9, 9
	v_writelane_b32 v248, s10, 10
	v_writelane_b32 v248, s11, 11
	v_writelane_b32 v248, s12, 12
	v_writelane_b32 v248, s13, 13
	v_writelane_b32 v248, s14, 14
	v_writelane_b32 v248, s15, 15
	v_writelane_b32 v248, s16, 16
	v_writelane_b32 v248, s17, 17
	v_writelane_b32 v248, s18, 18
	v_writelane_b32 v248, s19, 19
	v_writelane_b32 v248, s20, 20
	v_writelane_b32 v248, s21, 21
	v_writelane_b32 v248, s22, 22
	v_writelane_b32 v248, s23, 23
	v_writelane_b32 v248, s24, 24
	v_writelane_b32 v248, s25, 25
	v_writelane_b32 v248, s26, 26
	v_writelane_b32 v248, s27, 27
	v_writelane_b32 v248, s28, 28
	v_writelane_b32 v248, s29, 29
	v_writelane_b32 v248, s30, 30
	v_writelane_b32 v248, s31, 31
	v_writelane_b32 v248, s32, 32
	v_writelane_b32 v248, s33, 33
	v_writelane_b32 v248, s34, 34
	v_writelane_b32 v248, s35, 35
	v_writelane_b32 v248, s36, 36
	v_writelane_b32 v248, s37, 37
	v_writelane_b32 v248, s38, 38
	v_writelane_b32 v248, s39, 39
	v_writelane_b32 v248, s40, 40
	v_writelane_b32 v248, s41, 41
	v_writelane_b32 v248, s42, 42
	v_writelane_b32 v248, s43, 43
	v_writelane_b32 v248, s44, 44
	v_writelane_b32 v248, s45, 45
	v_writelane_b32 v248, s46, 46
	v_writelane_b32 v248, s47, 47
	v_writelane_b32 v248, s48, 48
	v_writelane_b32 v248, s49, 49
	v_writelane_b32 v248, s50, 50
	v_writelane_b32 v248, s51, 51
	v_writelane_b32 v248, s52, 52
	v_writelane_b32 v248, s53, 53
	v_writelane_b32 v248, s54, 54
	v_writelane_b32 v248, s55, 55
	v_writelane_b32 v248, s56, 56
	v_writelane_b32 v248, s57, 57
	v_writelane_b32 v248, s58, 58
	v_writelane_b32 v248, s59, 59
	v_writelane_b32 v248, s60, 60
	v_writelane_b32 v248, s61, 61
	v_writelane_b32 v248, s62, 62
	v_writelane_b32 v248, s63, 63
	v_writelane_b32 v249, s64, 0
	v_writelane_b32 v249, s65, 1
	v_writelane_b32 v249, s66, 2
	v_writelane_b32 v249, s67, 3
	v_writelane_b32 v249, s68, 4
	v_writelane_b32 v249, s69, 5
	v_writelane_b32 v249, s70, 6
	v_writelane_b32 v249, s71, 7
	v_writelane_b32 v249, s72, 8
	v_writelane_b32 v249, s73, 9
	v_writelane_b32 v249, s74, 10
	v_writelane_b32 v249, s75, 11
	v_writelane_b32 v249, s76, 12
	v_writelane_b32 v249, s77, 13
	v_writelane_b32 v249, s78, 14
	v_writelane_b32 v249, s79, 15
	v_writelane_b32 v249, s80, 16
	v_writelane_b32 v249, s81, 17
	v_writelane_b32 v249, s82, 18
	v_writelane_b32 v249, s83, 19
	v_writelane_b32 v249, s84, 20
	v_writelane_b32 v249, s85, 21
	v_writelane_b32 v249, s86, 22
	v_writelane_b32 v249, s87, 23
	v_writelane_b32 v249, s88, 24
	v_writelane_b32 v249, s89, 25
	v_writelane_b32 v249, s90, 26
	v_writelane_b32 v249, s91, 27
	v_writelane_b32 v249, s92, 28
	v_writelane_b32 v249, s93, 29
	v_writelane_b32 v249, s94, 30
	v_writelane_b32 v249, s95, 31
	v_writelane_b32 v249, s96, 32
	v_writelane_b32 v249, s97, 33
	v_readlane_b32 s1, v250, 9
	v_readlane_b32 s86, v250, 10
	v_readlane_b32 s87, v250, 11
	s_sub_i32 s0, s2, s99
	s_lshl_b32 s0, s0, 3
	s_nop 1
	s_add_i32 s12, s0, s1
	s_add_i32 s12, s12, 0x14a80
	s_movk_i32 s14, 0x80
	s_mov_b32 s100, 0x1aa80
	s_mov_b32 s101, 1
	s_branch .Lcv_entry
